# same as scan two-ahead version; grid barrier spin bound raised to 2^20 polls
# speedup vs baseline: 1.0029x; 1.0029x over previous
; __device__ __forceinline__ unsigned xb_ld(unsigned* p)              { return __hip_atomic_load(p, __ATOMIC_RELAXED, __HIP_MEMORY_SCOPE_AGENT); }
; __device__ __forceinline__ unsigned xb_add(unsigned* p, unsigned v) { return __hip_atomic_fetch_add(p, v, __ATOMIC_RELAXED, __HIP_MEMORY_SCOPE_AGENT); }
; #define XB_SPIN(cond, bar) do { unsigned _sp = 0; while (cond) { __builtin_amdgcn_s_sleep(1); \
;     if ((++_sp & 255u) == 0u) { if (xb_ld(&(bar)[XB_TMO])) break; if (_sp > XB_SPIN_CAP) { atomicAdd(&(bar)[XB_TMO], 1u); break; } } } } while (0)
; __device__ __forceinline__ void xcd_barrier(const XcdBarrier& b) {
;     ...
;             else XB_SPIN(xb_ld(&bar[XB_TOPGEN]) == tg, bar);
;             __builtin_amdgcn_fence(__ATOMIC_ACQUIRE, "agent");
;             xb_add(&bar[XB_XGEN(b.x)], 1u);
;             asm volatile("s_waitcnt vmcnt(0)" ::: "memory");
;         } else {
;             XB_SPIN(xb_ld(&bar[XB_XGEN(b.x)]) == gen, bar);
.Lxb_spin_0:
	global_load_dword v0, v3, s[16:17] sc1
	s_waitcnt vmcnt(0)
	v_readfirstlane_b32 s19, v0
	s_cmp_ge_u32 s19, s15
	s_cbranch_scc1 .Lxb_done_0
	s_sleep 1
	s_add_i32 s18, s18, 1
	s_cmp_lt_u32 s18, 0x100000
	s_cbranch_scc1 .Lxb_spin_0
